# GEMM P8 K-loop only: saddr LDS-DMA + 3 of 6 SP2 pieces issued inside the MFMA block; attention LDS prefetch depth
# speedup vs baseline: 1.0003x; 1.0003x over previous
.LBB0_584:
	s_mov_b32 s84, 64
	s_and_b64 vcc, exec, s[18:19]
	s_cbranch_vccz .LBB0_586
	s_add_i32 s4, s29, 0xfffffe00
	s_lshr_b32 s4, s4, 3
	s_lshl_b32 s5, s29, 2
	s_and_b32 s4, s4, 0x1fffffe0
	s_and_b32 s6, s5, 24
	s_or_b32 s4, s4, s6
	s_bfe_u32 s6, s29, 0x20006
	s_lshr_b32 s26, s4, 3
	s_and_b32 s7, s5, 4
	s_lshr_b32 s7, s7, 1
	s_and_b32 s4, s6, 1
	s_or_b32 s4, s4, s7
	s_and_b32 s7, s6, 2
	s_lshl_b32 s7, s7, 1
	s_or_b32 s4, s4, s7
	s_mul_i32 s6, s26, 0x1800000
	s_mul_hi_u32 s5, s26, 0x1800000
	s_add_u32 s6, s65, s6
	s_addc_u32 s8, s66, s5
	s_lshl_b32 s16, s4, 8
	s_add_u32 s4, s6, s16
	s_addc_u32 s5, s8, 0
	s_lshl_b32 s7, s7, 6
	s_add_u32 s9, s6, s7
	s_addc_u32 s12, s8, 0
	s_add_u32 s6, s9, 0x800
	s_addc_u32 s7, s12, 0
	s_add_u32 s8, s9, 0xa00
	s_addc_u32 s9, s12, 0
	s_lshl_b64 s[12:13], s[26:27], 22
	s_add_u32 s12, s73, s12
	s_addc_u32 s13, s74, s13
	s_add_u32 s12, s12, s16
	s_addc_u32 s13, s13, 0
	s_lshl_b32 s16, s29, 5
	s_and_b32 s82, s16, 0x700
	s_mov_b64 s[16:17], 0
	s_movk_i32 s26, 0x1800
	s_movk_i32 s81, 0x400
	s_movk_i32 s80, 0x800
	s_mov_b32 s20, 0
	s_mov_b32 s85, 32
	s_mov_b32 s84, 2.0
	s_mov_b32 s83, 0

.LBB0_590:
	ds_read_b128 v[232:235], v185 offset:49152
	ds_read_b128 v[250:253], v185 offset:57344
	ds_read_b128 v[168:171], v186 offset:49152
	ds_read_b128 v[172:175], v186 offset:57344
	v_cndmask_b32_e64 v236, 0, 1, s[18:19]
	v_cmp_ne_u32_e64 s[6:7], 1, v236
	s_andn2_b64 vcc, exec, s[18:19]
	s_waitcnt lgkmcnt(3)
	v_mfma_f32_32x32x16_bf16 v[82:97], v[232:235], v[142:145], 0
	ds_read_b128 v[232:235], v187 offset:49152
	s_waitcnt lgkmcnt(3)
	v_mfma_f32_32x32x16_bf16 v[66:81], v[250:253], v[142:145], 0
	ds_read_b128 v[250:253], v187 offset:57344
	s_waitcnt lgkmcnt(3)
	v_mfma_f32_32x32x16_bf16 v[82:97], v[168:171], v[138:141], v[82:97]
	ds_read_b128 v[168:171], v188 offset:49152
	s_waitcnt lgkmcnt(3)
	v_mfma_f32_32x32x16_bf16 v[66:81], v[172:175], v[138:141], v[66:81]
	ds_read_b128 v[172:175], v188 offset:57344
	s_waitcnt lgkmcnt(3)
	v_mfma_f32_32x32x16_bf16 v[82:97], v[232:235], v[134:137], v[82:97]
	ds_read_b128 v[232:235], v189 offset:49152
	s_waitcnt lgkmcnt(3)
	v_mfma_f32_32x32x16_bf16 v[66:81], v[250:253], v[134:137], v[66:81]
	ds_read_b128 v[250:253], v189 offset:57344
	s_waitcnt lgkmcnt(3)
	v_mfma_f32_32x32x16_bf16 v[82:97], v[168:171], v[130:133], v[82:97]
	ds_read_b128 v[168:171], v205 offset:49152
	s_waitcnt lgkmcnt(3)
	v_mfma_f32_32x32x16_bf16 v[66:81], v[172:175], v[130:133], v[66:81]
	ds_read_b128 v[172:175], v205 offset:57344
	s_waitcnt lgkmcnt(3)
	v_mfma_f32_32x32x16_bf16 v[82:97], v[232:235], v[126:129], v[82:97]
	ds_read_b128 v[232:235], v206 offset:49152
	s_waitcnt lgkmcnt(3)
	v_mfma_f32_32x32x16_bf16 v[66:81], v[250:253], v[126:129], v[66:81]
	ds_read_b128 v[250:253], v206 offset:57344
	s_waitcnt lgkmcnt(3)
	v_mfma_f32_32x32x16_bf16 v[82:97], v[168:171], v[122:125], v[82:97]
	ds_read_b128 v[168:171], v207 offset:49152
	s_waitcnt lgkmcnt(3)
	v_mfma_f32_32x32x16_bf16 v[66:81], v[172:175], v[122:125], v[66:81]
	ds_read_b128 v[172:175], v207 offset:57344
	s_waitcnt lgkmcnt(3)
	v_mfma_f32_32x32x16_bf16 v[82:97], v[232:235], v[118:121], v[82:97]
	s_waitcnt lgkmcnt(2)
	v_mfma_f32_32x32x16_bf16 v[66:81], v[250:253], v[118:121], v[66:81]
	s_waitcnt lgkmcnt(1)
	v_mfma_f32_32x32x16_bf16 v[82:97], v[168:171], v[114:117], v[82:97]
	s_waitcnt lgkmcnt(0)
	v_mfma_f32_32x32x16_bf16 v[66:81], v[172:175], v[114:117], v[66:81]
	s_cbranch_vccnz .LBB0_592
	v_add_u32_e32 v232, 27, v215
	v_cmp_lt_i32_e32 vcc, s84, v232
	v_cmp_gt_i32_e64 s[8:9], s88, v232
	s_or_b64 vcc, vcc, s[8:9]
	v_add_u32_e32 v232, -5, v215
	s_nop 2
	v_cndmask_b32_e32 v82, v82, v203, vcc
	v_cmp_lt_i32_e32 vcc, s84, v232
	v_cmp_gt_i32_e64 s[8:9], s88, v232
	s_or_b64 vcc, vcc, s[8:9]
	v_add_u32_e32 v232, 26, v215
	v_cndmask_b32_e32 v66, v66, v203, vcc
	v_cmp_lt_i32_e32 vcc, s84, v232
	v_cmp_gt_i32_e64 s[8:9], s88, v232
	s_or_b64 vcc, vcc, s[8:9]
	v_add_u32_e32 v232, -6, v215
	v_cndmask_b32_e32 v83, v83, v203, vcc
	v_cmp_lt_i32_e32 vcc, s84, v232
	v_cmp_gt_i32_e64 s[8:9], s88, v232
	s_or_b64 vcc, vcc, s[8:9]
	v_add_u32_e32 v232, 25, v215
	v_cndmask_b32_e32 v67, v67, v203, vcc
	v_cmp_lt_i32_e32 vcc, s84, v232
	v_cmp_gt_i32_e64 s[8:9], s88, v232
	s_or_b64 vcc, vcc, s[8:9]
	v_add_u32_e32 v232, -7, v215
	v_cndmask_b32_e32 v84, v84, v203, vcc
	v_cmp_lt_i32_e32 vcc, s84, v232
	v_cmp_gt_i32_e64 s[8:9], s88, v232
	s_or_b64 vcc, vcc, s[8:9]
	v_add_u32_e32 v232, 24, v215
	v_cndmask_b32_e32 v68, v68, v203, vcc
	v_cmp_lt_i32_e32 vcc, s84, v232
	v_cmp_gt_i32_e64 s[8:9], s88, v232
	s_or_b64 vcc, vcc, s[8:9]
	v_add_u32_e32 v232, -8, v215
	v_cndmask_b32_e32 v85, v85, v203, vcc
	v_cmp_lt_i32_e32 vcc, s84, v232
	v_cmp_gt_i32_e64 s[8:9], s88, v232
	s_or_b64 vcc, vcc, s[8:9]
	v_add_u32_e32 v232, 19, v215
	v_cndmask_b32_e32 v69, v69, v203, vcc
	v_cmp_lt_i32_e32 vcc, s84, v232
	v_cmp_gt_i32_e64 s[8:9], s88, v232
	s_or_b64 vcc, vcc, s[8:9]
	v_add_u32_e32 v232, -13, v215
	v_cndmask_b32_e32 v86, v86, v203, vcc
	v_cmp_lt_i32_e32 vcc, s84, v232
	v_cmp_gt_i32_e64 s[8:9], s88, v232
	s_or_b64 vcc, vcc, s[8:9]
	v_add_u32_e32 v232, 18, v215
	v_cndmask_b32_e32 v70, v70, v203, vcc
	v_cmp_lt_i32_e32 vcc, s84, v232
	v_cmp_gt_i32_e64 s[8:9], s88, v232
	s_or_b64 vcc, vcc, s[8:9]
	v_add_u32_e32 v232, -14, v215
	v_cndmask_b32_e32 v87, v87, v203, vcc
	v_cmp_lt_i32_e32 vcc, s84, v232
	v_cmp_gt_i32_e64 s[8:9], s88, v232
	s_or_b64 vcc, vcc, s[8:9]
	v_add_u32_e32 v232, 17, v215
	v_cndmask_b32_e32 v71, v71, v203, vcc
	v_cmp_lt_i32_e32 vcc, s84, v232
	v_cmp_gt_i32_e64 s[8:9], s88, v232
	s_or_b64 vcc, vcc, s[8:9]
	v_add_u32_e32 v232, -15, v215
	v_cndmask_b32_e32 v88, v88, v203, vcc
	v_cmp_lt_i32_e32 vcc, s84, v232
	v_cmp_gt_i32_e64 s[8:9], s88, v232
	s_or_b64 vcc, vcc, s[8:9]
	v_add_u32_e32 v232, 16, v215
	v_cndmask_b32_e32 v72, v72, v203, vcc
	v_cmp_lt_i32_e32 vcc, s84, v232
	v_cmp_gt_i32_e64 s[8:9], s88, v232
	s_or_b64 vcc, vcc, s[8:9]
	v_add_u32_e32 v232, -16, v215
	v_cndmask_b32_e32 v89, v89, v203, vcc
	v_cmp_lt_i32_e32 vcc, s84, v232
	v_cmp_gt_i32_e64 s[8:9], s88, v232
	s_or_b64 vcc, vcc, s[8:9]
	v_add_u32_e32 v232, 11, v215
	v_cndmask_b32_e32 v73, v73, v203, vcc
	v_cmp_lt_i32_e32 vcc, s84, v232
	v_cmp_gt_i32_e64 s[8:9], s88, v232
	s_or_b64 vcc, vcc, s[8:9]
	v_subrev_u32_e32 v232, 21, v215
	v_cndmask_b32_e32 v90, v90, v203, vcc
	v_cmp_lt_i32_e32 vcc, s84, v232
	v_cmp_gt_i32_e64 s[8:9], s88, v232
	s_or_b64 vcc, vcc, s[8:9]
	v_add_u32_e32 v232, 10, v215
	v_cndmask_b32_e32 v74, v74, v203, vcc
	v_cmp_lt_i32_e32 vcc, s84, v232
	v_cmp_gt_i32_e64 s[8:9], s88, v232
	s_or_b64 vcc, vcc, s[8:9]
	v_subrev_u32_e32 v232, 22, v215
	v_cndmask_b32_e32 v91, v91, v203, vcc
	v_cmp_lt_i32_e32 vcc, s84, v232
	v_cmp_gt_i32_e64 s[8:9], s88, v232
	s_or_b64 vcc, vcc, s[8:9]
	v_add_u32_e32 v232, 9, v215
	v_cndmask_b32_e32 v75, v75, v203, vcc
	v_cmp_lt_i32_e32 vcc, s84, v232
	v_cmp_gt_i32_e64 s[8:9], s88, v232
	s_or_b64 vcc, vcc, s[8:9]
	v_subrev_u32_e32 v232, 23, v215
	v_cndmask_b32_e32 v92, v92, v203, vcc
	v_cmp_lt_i32_e32 vcc, s84, v232
	v_cmp_gt_i32_e64 s[8:9], s88, v232
	s_or_b64 vcc, vcc, s[8:9]
	v_add_u32_e32 v232, 8, v215
	v_cndmask_b32_e32 v76, v76, v203, vcc
	v_cmp_lt_i32_e32 vcc, s84, v232
	v_cmp_gt_i32_e64 s[8:9], s88, v232
	s_or_b64 vcc, vcc, s[8:9]
	v_subrev_u32_e32 v232, 24, v215
	v_cndmask_b32_e32 v93, v93, v203, vcc
	v_cmp_lt_i32_e32 vcc, s84, v232
	v_cmp_gt_i32_e64 s[8:9], s88, v232
	s_or_b64 vcc, vcc, s[8:9]
	v_add_u32_e32 v232, 3, v215
	v_cndmask_b32_e32 v77, v77, v203, vcc
	v_cmp_lt_i32_e32 vcc, s84, v232
	v_cmp_gt_i32_e64 s[8:9], s88, v232
	s_or_b64 vcc, vcc, s[8:9]
	v_subrev_u32_e32 v232, 29, v215
	v_cndmask_b32_e32 v94, v94, v203, vcc
	v_cmp_lt_i32_e32 vcc, s84, v232
	v_cmp_gt_i32_e64 s[8:9], s88, v232
	s_or_b64 vcc, vcc, s[8:9]
	v_add_u32_e32 v232, 2, v215
	v_cndmask_b32_e32 v78, v78, v203, vcc
	v_cmp_lt_i32_e32 vcc, s84, v232
	v_cmp_gt_i32_e64 s[8:9], s88, v232
	s_or_b64 vcc, vcc, s[8:9]
	v_subrev_u32_e32 v232, 30, v215
	v_cndmask_b32_e32 v95, v95, v203, vcc
	v_cmp_lt_i32_e32 vcc, s84, v232
	v_cmp_gt_i32_e64 s[8:9], s88, v232
	s_or_b64 vcc, vcc, s[8:9]
	v_add_u32_e32 v232, 1, v215
	v_cndmask_b32_e32 v79, v79, v203, vcc
	v_cmp_lt_i32_e32 vcc, s84, v232
	v_cmp_gt_i32_e64 s[8:9], s88, v232
	s_or_b64 vcc, vcc, s[8:9]
	v_subrev_u32_e32 v232, 31, v215
	v_cndmask_b32_e32 v96, v96, v203, vcc
	v_cmp_lt_i32_e32 vcc, s84, v232
	v_cmp_gt_i32_e64 s[8:9], s88, v232
	s_or_b64 vcc, vcc, s[8:9]
	v_cndmask_b32_e32 v80, v80, v203, vcc
	v_cmp_lt_i32_e32 vcc, s84, v215
	v_cmp_gt_i32_e64 s[8:9], s88, v215
	s_or_b64 vcc, vcc, s[8:9]
	v_subrev_u32_e32 v232, 32, v215
	v_cndmask_b32_e32 v97, v97, v203, vcc
	v_cmp_lt_i32_e32 vcc, s84, v232
	v_cmp_gt_i32_e64 s[8:9], s88, v232
	s_or_b64 vcc, vcc, s[8:9]
	v_cndmask_b32_e32 v81, v81, v203, vcc
.LBB0_592:
	v_add_f32_e32 v232, 0, v223
	v_add_f32_e32 v232, v225, v232
	v_add_f32_e32 v232, v226, v232
	v_add_f32_e32 v232, v227, v232
	v_add_f32_e32 v232, v228, v232
	v_add_f32_e32 v232, v229, v232
	v_add_f32_e32 v232, v230, v232
	v_add_f32_e32 v232, v231, v232
	v_add_f32_e32 v232, v216, v232
	v_add_f32_e32 v232, v217, v232
	v_add_f32_e32 v232, v218, v232
	v_add_f32_e32 v232, v219, v232
	v_exp_f32_e32 v112, v112
	v_add_f32_e32 v232, v220, v232
	v_exp_f32_e32 v113, v113
	v_add_f32_e32 v232, v221, v232
	v_exp_f32_e32 v110, v110
	v_add_f32_e32 v232, v222, v232
	v_exp_f32_e32 v111, v111
	v_add_f32_e32 v232, v224, v232
	v_exp_f32_e32 v108, v108
	v_add_f32_e32 v232, v112, v232
	v_exp_f32_e32 v109, v109
	v_add_f32_e32 v232, v113, v232
	v_exp_f32_e32 v106, v106
	v_add_f32_e32 v232, v110, v232
	v_exp_f32_e32 v107, v107
	v_add_f32_e32 v232, v111, v232
	v_exp_f32_e32 v104, v104
	v_add_f32_e32 v232, v108, v232
	v_exp_f32_e32 v105, v105
	v_add_f32_e32 v232, v109, v232
	v_exp_f32_e32 v102, v102
	v_add_f32_e32 v232, v106, v232
	v_exp_f32_e32 v103, v103
	v_add_f32_e32 v232, v107, v232
	v_exp_f32_e32 v100, v100
	v_add_f32_e32 v232, v104, v232
	v_exp_f32_e32 v101, v101
	v_add_f32_e32 v232, v105, v232
	v_exp_f32_e32 v98, v98
	v_add_f32_e32 v232, v102, v232
	v_exp_f32_e32 v99, v99
	v_add_f32_e32 v232, v103, v232
	v_add_f32_e32 v232, v100, v232
	v_add_f32_e32 v232, v101, v232
	v_add_f32_e32 v232, v98, v232
	v_add_f32_e32 v232, v99, v232
	v_mov_b32_e32 v233, v232
	v_cvt_pk_bf16_f32 v235, v226, v227
	v_cvt_pk_bf16_f32 v237, v230, v231
	v_cvt_pk_bf16_f32 v216, v216, v217
	v_cvt_pk_bf16_f32 v217, v218, v219
	v_cvt_pk_bf16_f32 v218, v220, v221
	v_permlane32_swap_b32_e32 v232, v233
	v_cvt_pk_bf16_f32 v234, v223, v225
	v_cvt_pk_bf16_f32 v236, v228, v229
	v_permlane32_swap_b32_e32 v235, v237
	v_cvt_pk_bf16_f32 v219, v222, v224
	v_permlane32_swap_b32_e32 v216, v218
	v_cvt_pk_bf16_f32 v220, v112, v113
	v_cvt_pk_bf16_f32 v221, v110, v111
	v_cvt_pk_bf16_f32 v222, v108, v109
	v_cvt_pk_bf16_f32 v223, v106, v107
	v_cvt_pk_bf16_f32 v224, v104, v105
	v_cvt_pk_bf16_f32 v225, v102, v103
	v_cvt_pk_bf16_f32 v226, v100, v101
	v_cvt_pk_bf16_f32 v227, v98, v99
	v_permlane32_swap_b32_e32 v234, v236
	v_permlane32_swap_b32_e32 v217, v219
	v_permlane32_swap_b32_e32 v220, v222
	v_permlane32_swap_b32_e32 v221, v223
	v_permlane32_swap_b32_e32 v224, v226
	v_permlane32_swap_b32_e32 v225, v227
	v_lshl_add_u64 v[98:99], v[156:157], 0, s[22:23]
	v_lshl_add_u64 v[102:103], v[158:159], 0, s[22:23]
	v_lshl_add_u64 v[106:107], v[160:161], 0, s[22:23]
	v_lshl_add_u64 v[110:111], v[162:163], 0, s[22:23]
	global_load_dwordx4 v[98:101], v[98:99], off
	s_nop 0
	global_load_dwordx4 v[102:105], v[102:103], off
	s_nop 0
	global_load_dwordx4 v[106:109], v[106:107], off
	s_nop 0
	global_load_dwordx4 v[110:113], v[110:111], off
	ds_read_b64_tr_b16 v[228:229], v184 offset:0
	ds_read_b64_tr_b16 v[230:231], v184 offset:2048
	ds_read_b64_tr_b16 v[242:243], v184 offset:4096
	ds_read_b64_tr_b16 v[244:245], v184 offset:6144
	ds_read_b64_tr_b16 v[196:197], v184 offset:8192
	ds_read_b64_tr_b16 v[198:199], v184 offset:10240
	s_waitcnt lgkmcnt(4)
	v_mfma_f32_32x32x16_bf16 v[50:65], v[234:237], v[228:231], v[50:65]
	ds_read_b64_tr_b16 v[238:239], v184 offset:12288
	ds_read_b64_tr_b16 v[240:241], v184 offset:14336
	s_waitcnt lgkmcnt(4)
	v_mfma_f32_32x32x16_bf16 v[50:65], v[216:219], v[242:245], v[50:65]
	ds_read_b64_tr_b16 v[228:229], v184 offset:512
	ds_read_b64_tr_b16 v[230:231], v184 offset:2560
	s_waitcnt lgkmcnt(4)
	v_mfma_f32_32x32x16_bf16 v[50:65], v[220:223], v[196:199], v[50:65]
	ds_read_b64_tr_b16 v[242:243], v184 offset:4608
	ds_read_b64_tr_b16 v[244:245], v184 offset:6656
	s_waitcnt lgkmcnt(4)
	v_mfma_f32_32x32x16_bf16 v[50:65], v[224:227], v[238:241], v[50:65]
	ds_read_b64_tr_b16 v[196:197], v184 offset:8704
	ds_read_b64_tr_b16 v[198:199], v184 offset:10752
	s_waitcnt lgkmcnt(4)
	v_mfma_f32_32x32x16_bf16 v[34:49], v[234:237], v[228:231], v[34:49]
	ds_read_b64_tr_b16 v[238:239], v184 offset:12800
	ds_read_b64_tr_b16 v[240:241], v184 offset:14848
	s_waitcnt lgkmcnt(4)
	v_mfma_f32_32x32x16_bf16 v[34:49], v[216:219], v[242:245], v[34:49]
	ds_read_b64_tr_b16 v[228:229], v184 offset:1024
	ds_read_b64_tr_b16 v[230:231], v184 offset:3072
	s_waitcnt lgkmcnt(4)
	v_mfma_f32_32x32x16_bf16 v[34:49], v[220:223], v[196:199], v[34:49]
	ds_read_b64_tr_b16 v[242:243], v184 offset:5120
	ds_read_b64_tr_b16 v[244:245], v184 offset:7168
	s_waitcnt lgkmcnt(4)
	v_mfma_f32_32x32x16_bf16 v[34:49], v[224:227], v[238:241], v[34:49]
	ds_read_b64_tr_b16 v[196:197], v184 offset:9216
	ds_read_b64_tr_b16 v[198:199], v184 offset:11264
	s_waitcnt lgkmcnt(4)
	v_mfma_f32_32x32x16_bf16 v[18:33], v[234:237], v[228:231], v[18:33]
	ds_read_b64_tr_b16 v[238:239], v184 offset:13312
	ds_read_b64_tr_b16 v[240:241], v184 offset:15360
	s_waitcnt lgkmcnt(4)
	v_mfma_f32_32x32x16_bf16 v[18:33], v[216:219], v[242:245], v[18:33]
	ds_read_b64_tr_b16 v[228:229], v184 offset:1536
	ds_read_b64_tr_b16 v[230:231], v184 offset:3584
	s_waitcnt lgkmcnt(4)
	v_mfma_f32_32x32x16_bf16 v[18:33], v[220:223], v[196:199], v[18:33]
	ds_read_b64_tr_b16 v[242:243], v184 offset:5632
	ds_read_b64_tr_b16 v[244:245], v184 offset:7680
	s_waitcnt lgkmcnt(4)
	v_mfma_f32_32x32x16_bf16 v[18:33], v[224:227], v[238:241], v[18:33]
	ds_read_b64_tr_b16 v[196:197], v184 offset:9728
	ds_read_b64_tr_b16 v[198:199], v184 offset:11776
	s_waitcnt lgkmcnt(4)
	v_mfma_f32_32x32x16_bf16 v[2:17], v[234:237], v[228:231], v[2:17]
	ds_read_b64_tr_b16 v[238:239], v184 offset:13824
	ds_read_b64_tr_b16 v[240:241], v184 offset:15872
	s_waitcnt lgkmcnt(4)
	v_mfma_f32_32x32x16_bf16 v[2:17], v[216:219], v[242:245], v[2:17]
	v_max_f32_e32 v216, v83, v83
	v_max_f32_e32 v217, v82, v82
	v_max_f32_e32 v216, v217, v216
	v_max3_f32 v216, v216, v84, v85
	v_max3_f32 v216, v216, v86, v87
	v_max3_f32 v216, v216, v88, v89
	v_max3_f32 v216, v216, v90, v91
	v_max3_f32 v216, v216, v92, v93
	v_max3_f32 v216, v216, v94, v95
	v_max3_f32 v216, v216, v96, v97
	v_max3_f32 v216, v216, v66, v67
	v_max3_f32 v216, v216, v68, v69
	v_max3_f32 v216, v216, v70, v71
	v_max3_f32 v216, v216, v72, v73
	v_max3_f32 v216, v216, v74, v75
	v_max3_f32 v216, v216, v76, v77
	v_max3_f32 v216, v216, v78, v79
	s_waitcnt lgkmcnt(2)
	v_mfma_f32_32x32x16_bf16 v[2:17], v[220:223], v[196:199], v[2:17]
	v_max3_f32 v216, v216, v80, v81
	v_mov_b32_e32 v217, v216
	s_nop 1
	v_permlane32_swap_b32_e32 v216, v217
	v_max_f32_e32 v217, v217, v217
	v_max_f32_e32 v216, v216, v216
	v_max_f32_e32 v216, v216, v217
	v_sub_f32_e32 v217, v216, v212
	v_cmp_ge_f32_e32 vcc, s40, v217
	v_max_f32_e32 v217, v212, v212
	v_max_f32_e32 v216, v217, v216
	s_waitcnt lgkmcnt(0)
	v_mfma_f32_32x32x16_bf16 v[2:17], v[224:227], v[238:241], v[2:17]
	v_sub_f32_e32 v217, v212, v216
	v_mul_f32_e32 v217, 0x3e0293ee, v217
	s_barrier
	s_waitcnt vmcnt(3)
	ds_write_b128 v208, v[98:101]
	s_waitcnt vmcnt(2)
	ds_write_b128 v209, v[102:105]
	s_waitcnt vmcnt(1)
	ds_write_b128 v210, v[106:109] offset:32768
	s_waitcnt vmcnt(0)
	ds_write_b128 v211, v[110:113] offset:32768
	v_exp_f32_e32 v98, v217
	s_cmp_eq_u64 vcc, exec
	s_cselect_b64 s[8:9], -1, 0
	v_cndmask_b32_e64 v235, v98, 1.0, s[8:9]
	v_cmp_gt_f32_e32 vcc, 1.0, v235
	s_cbranch_vccz .LBB0_596
	s_and_saveexec_b64 s[60:61], s[4:5]
	ds_write_b32 v183, v235 offset:128
	s_or_b64 exec, exec, s[60:61]
	s_waitcnt lgkmcnt(0)
	v_add_u32_e32 v110, v181, v146
	ds_read_b128 v[98:101], v110 offset:224
	ds_read_b128 v[102:105], v110 offset:192
	ds_read_b128 v[106:109], v110 offset:160
	ds_read_b128 v[110:113], v110 offset:128
	s_waitcnt lgkmcnt(3)
	v_pk_mul_f32 v[62:63], v[62:63], v[98:99]
	s_waitcnt lgkmcnt(2)
	v_pk_mul_f32 v[58:59], v[58:59], v[102:103]
	s_waitcnt lgkmcnt(1)
	v_pk_mul_f32 v[54:55], v[54:55], v[106:107]
	v_pk_mul_f32 v[64:65], v[64:65], v[100:101]
	v_pk_mul_f32 v[60:61], v[60:61], v[104:105]
	v_pk_mul_f32 v[56:57], v[56:57], v[108:109]
	s_waitcnt lgkmcnt(0)
	v_pk_mul_f32 v[52:53], v[52:53], v[112:113]
	v_pk_mul_f32 v[50:51], v[50:51], v[110:111]
	v_pk_mul_f32 v[46:47], v[46:47], v[98:99]
	v_pk_mul_f32 v[42:43], v[42:43], v[102:103]
	v_pk_mul_f32 v[38:39], v[38:39], v[106:107]
	v_pk_mul_f32 v[48:49], v[48:49], v[100:101]
	v_pk_mul_f32 v[44:45], v[44:45], v[104:105]
	v_pk_mul_f32 v[40:41], v[40:41], v[108:109]
	v_pk_mul_f32 v[36:37], v[36:37], v[112:113]
	v_pk_mul_f32 v[34:35], v[34:35], v[110:111]
	v_pk_mul_f32 v[30:31], v[30:31], v[98:99]
	v_pk_mul_f32 v[26:27], v[26:27], v[102:103]
	v_pk_mul_f32 v[22:23], v[22:23], v[106:107]
	v_pk_mul_f32 v[32:33], v[32:33], v[100:101]
	v_pk_mul_f32 v[28:29], v[28:29], v[104:105]
	v_pk_mul_f32 v[24:25], v[24:25], v[108:109]
	v_pk_mul_f32 v[20:21], v[20:21], v[112:113]
	v_pk_mul_f32 v[18:19], v[18:19], v[110:111]
	v_pk_mul_f32 v[14:15], v[14:15], v[98:99]
	v_pk_mul_f32 v[10:11], v[10:11], v[102:103]
	v_pk_mul_f32 v[6:7], v[6:7], v[106:107]
	v_pk_mul_f32 v[16:17], v[16:17], v[100:101]
	v_pk_mul_f32 v[12:13], v[12:13], v[104:105]
	v_pk_mul_f32 v[8:9], v[8:9], v[108:109]
	v_pk_mul_f32 v[4:5], v[4:5], v[112:113]
	v_pk_mul_f32 v[2:3], v[2:3], v[110:111]
.LBB0_596:
	v_cndmask_b32_e64 v212, v216, v212, s[8:9]
	v_mul_f32_e32 v227, 0xbe0293ee, v212
	v_fmamk_f32 v82, v82, 0x3e0293ee, v227
	v_fmamk_f32 v83, v83, 0x3e0293ee, v227
	v_fmamk_f32 v84, v84, 0x3e0293ee, v227
	v_fmamk_f32 v85, v85, 0x3e0293ee, v227
	v_fmamk_f32 v86, v86, 0x3e0293ee, v227
	v_fmamk_f32 v87, v87, 0x3e0293ee, v227
	v_fmamk_f32 v88, v88, 0x3e0293ee, v227
	v_fmamk_f32 v89, v89, 0x3e0293ee, v227
	v_fmamk_f32 v90, v90, 0x3e0293ee, v227
	v_fmamk_f32 v91, v91, 0x3e0293ee, v227
	v_fmamk_f32 v92, v92, 0x3e0293ee, v227
	v_fmamk_f32 v93, v93, 0x3e0293ee, v227
	v_fmamk_f32 v94, v94, 0x3e0293ee, v227
	v_fmamk_f32 v95, v95, 0x3e0293ee, v227
	v_fmamk_f32 v96, v96, 0x3e0293ee, v227
	v_fmamk_f32 v97, v97, 0x3e0293ee, v227
	v_fmamk_f32 v234, v66, 0x3e0293ee, v227
	v_fmamk_f32 v231, v68, 0x3e0293ee, v227
	v_fmamk_f32 v230, v70, 0x3e0293ee, v227
	v_fmamk_f32 v229, v72, 0x3e0293ee, v227
	v_fmamk_f32 v228, v74, 0x3e0293ee, v227
	v_exp_f32_e32 v72, v82
	v_exp_f32_e32 v217, v83
	v_exp_f32_e32 v218, v84
	v_exp_f32_e32 v221, v85
	v_exp_f32_e32 v222, v86
	v_exp_f32_e32 v224, v87
	v_exp_f32_e32 v225, v88
	v_exp_f32_e32 v226, v89
	v_exp_f32_e32 v66, v90
	v_exp_f32_e32 v68, v91
	v_exp_f32_e32 v70, v92
	v_exp_f32_e32 v74, v93
	v_exp_f32_e32 v216, v94
	v_exp_f32_e32 v219, v95
	v_exp_f32_e32 v220, v96
	v_exp_f32_e32 v223, v97
	v_fmamk_f32 v236, v76, 0x3e0293ee, v227
	v_fmamk_f32 v78, v78, 0x3e0293ee, v227
	v_fmamk_f32 v76, v80, 0x3e0293ee, v227
	s_waitcnt lgkmcnt(0)
	s_barrier
	ds_read_b128 v[242:245], v185 offset:32768
	ds_read_b128 v[250:253], v185 offset:40960
	ds_read_b128 v[168:171], v186 offset:32768
	ds_read_b128 v[172:175], v186 offset:40960
	s_and_b64 vcc, exec, s[6:7]
	s_waitcnt lgkmcnt(3)
	v_mfma_f32_32x32x16_bf16 v[98:113], v[242:245], v[142:145], 0
	ds_read_b128 v[242:245], v187 offset:32768
	s_waitcnt lgkmcnt(3)
	v_mfma_f32_32x32x16_bf16 v[82:97], v[250:253], v[142:145], 0
	ds_read_b128 v[250:253], v187 offset:40960
	s_waitcnt lgkmcnt(3)
	v_mfma_f32_32x32x16_bf16 v[98:113], v[168:171], v[138:141], v[98:113]
	ds_read_b128 v[168:171], v188 offset:32768
	s_waitcnt lgkmcnt(3)
	v_mfma_f32_32x32x16_bf16 v[82:97], v[172:175], v[138:141], v[82:97]
	ds_read_b128 v[172:175], v188 offset:40960
	s_waitcnt lgkmcnt(3)
	v_mfma_f32_32x32x16_bf16 v[98:113], v[242:245], v[134:137], v[98:113]
	ds_read_b128 v[242:245], v189 offset:32768
	s_waitcnt lgkmcnt(3)
	v_mfma_f32_32x32x16_bf16 v[82:97], v[250:253], v[134:137], v[82:97]
	ds_read_b128 v[250:253], v189 offset:40960
	s_waitcnt lgkmcnt(3)
	v_mfma_f32_32x32x16_bf16 v[98:113], v[168:171], v[130:133], v[98:113]
	ds_read_b128 v[168:171], v205 offset:32768
	s_waitcnt lgkmcnt(3)
	v_mfma_f32_32x32x16_bf16 v[82:97], v[172:175], v[130:133], v[82:97]
	ds_read_b128 v[172:175], v205 offset:40960
	s_waitcnt lgkmcnt(3)
	v_mfma_f32_32x32x16_bf16 v[98:113], v[242:245], v[126:129], v[98:113]
	ds_read_b128 v[242:245], v206 offset:32768
	s_waitcnt lgkmcnt(3)
	v_mfma_f32_32x32x16_bf16 v[82:97], v[250:253], v[126:129], v[82:97]
	ds_read_b128 v[250:253], v206 offset:40960
	s_waitcnt lgkmcnt(3)
	v_mfma_f32_32x32x16_bf16 v[98:113], v[168:171], v[122:125], v[98:113]
	ds_read_b128 v[168:171], v207 offset:32768
	s_waitcnt lgkmcnt(3)
	v_mfma_f32_32x32x16_bf16 v[82:97], v[172:175], v[122:125], v[82:97]
	ds_read_b128 v[172:175], v207 offset:40960
	s_waitcnt lgkmcnt(3)
	v_mfma_f32_32x32x16_bf16 v[98:113], v[242:245], v[118:121], v[98:113]
	s_waitcnt lgkmcnt(2)
	v_mfma_f32_32x32x16_bf16 v[82:97], v[250:253], v[118:121], v[82:97]
	s_waitcnt lgkmcnt(1)
	v_mfma_f32_32x32x16_bf16 v[98:113], v[168:171], v[114:117], v[98:113]
	s_waitcnt lgkmcnt(0)
	v_mfma_f32_32x32x16_bf16 v[82:97], v[172:175], v[114:117], v[82:97]
	s_cbranch_vccnz .LBB0_598
	v_subrev_u32_e32 v80, 37, v215
	v_cmp_lt_i32_e32 vcc, s84, v80
	v_cmp_gt_i32_e64 s[6:7], s88, v80
	s_or_b64 vcc, vcc, s[6:7]
	v_add_u32_e32 v80, 0xffffffbb, v215
	s_nop 2
	v_cndmask_b32_e32 v98, v98, v203, vcc
	v_cmp_lt_i32_e32 vcc, s84, v80
	v_cmp_gt_i32_e64 s[6:7], s88, v80
	s_or_b64 vcc, vcc, s[6:7]
	v_subrev_u32_e32 v80, 38, v215
	v_cndmask_b32_e32 v82, v82, v203, vcc
	v_cmp_lt_i32_e32 vcc, s84, v80
	v_cmp_gt_i32_e64 s[6:7], s88, v80
	s_or_b64 vcc, vcc, s[6:7]
	v_add_u32_e32 v80, 0xffffffba, v215
	v_cndmask_b32_e32 v99, v99, v203, vcc
	v_cmp_lt_i32_e32 vcc, s84, v80
	v_cmp_gt_i32_e64 s[6:7], s88, v80
	s_or_b64 vcc, vcc, s[6:7]
	v_subrev_u32_e32 v80, 39, v215
	v_cndmask_b32_e32 v83, v83, v203, vcc
	v_cmp_lt_i32_e32 vcc, s84, v80
	v_cmp_gt_i32_e64 s[6:7], s88, v80
	s_or_b64 vcc, vcc, s[6:7]
	v_add_u32_e32 v80, 0xffffffb9, v215
	v_cndmask_b32_e32 v100, v100, v203, vcc
	v_cmp_lt_i32_e32 vcc, s84, v80
	v_cmp_gt_i32_e64 s[6:7], s88, v80
	s_or_b64 vcc, vcc, s[6:7]
	v_subrev_u32_e32 v80, 40, v215
	v_cndmask_b32_e32 v84, v84, v203, vcc
	v_cmp_lt_i32_e32 vcc, s84, v80
	v_cmp_gt_i32_e64 s[6:7], s88, v80
	s_or_b64 vcc, vcc, s[6:7]
	v_add_u32_e32 v80, 0xffffffb8, v215
	v_cndmask_b32_e32 v101, v101, v203, vcc
	v_cmp_lt_i32_e32 vcc, s84, v80
	v_cmp_gt_i32_e64 s[6:7], s88, v80
	s_or_b64 vcc, vcc, s[6:7]
	v_subrev_u32_e32 v80, 45, v215
	v_cndmask_b32_e32 v85, v85, v203, vcc
	v_cmp_lt_i32_e32 vcc, s84, v80
	v_cmp_gt_i32_e64 s[6:7], s88, v80
	s_or_b64 vcc, vcc, s[6:7]
	v_add_u32_e32 v80, 0xffffffb3, v215
	v_cndmask_b32_e32 v102, v102, v203, vcc
	v_cmp_lt_i32_e32 vcc, s84, v80
	v_cmp_gt_i32_e64 s[6:7], s88, v80
	s_or_b64 vcc, vcc, s[6:7]
	v_subrev_u32_e32 v80, 46, v215
	v_cndmask_b32_e32 v86, v86, v203, vcc
	v_cmp_lt_i32_e32 vcc, s84, v80
	v_cmp_gt_i32_e64 s[6:7], s88, v80
	s_or_b64 vcc, vcc, s[6:7]
	v_add_u32_e32 v80, 0xffffffb2, v215
	v_cndmask_b32_e32 v103, v103, v203, vcc
	v_cmp_lt_i32_e32 vcc, s84, v80
	v_cmp_gt_i32_e64 s[6:7], s88, v80
	s_or_b64 vcc, vcc, s[6:7]
	v_subrev_u32_e32 v80, 47, v215
	v_cndmask_b32_e32 v87, v87, v203, vcc
	v_cmp_lt_i32_e32 vcc, s84, v80
	v_cmp_gt_i32_e64 s[6:7], s88, v80
	s_or_b64 vcc, vcc, s[6:7]
	v_add_u32_e32 v80, 0xffffffb1, v215
	v_cndmask_b32_e32 v104, v104, v203, vcc
	v_cmp_lt_i32_e32 vcc, s84, v80
	v_cmp_gt_i32_e64 s[6:7], s88, v80
	s_or_b64 vcc, vcc, s[6:7]
	v_subrev_u32_e32 v80, 48, v215
	v_cndmask_b32_e32 v88, v88, v203, vcc
	v_cmp_lt_i32_e32 vcc, s84, v80
	v_cmp_gt_i32_e64 s[6:7], s88, v80
	s_or_b64 vcc, vcc, s[6:7]
	v_add_u32_e32 v80, 0xffffffb0, v215
	v_cndmask_b32_e32 v105, v105, v203, vcc
	v_cmp_lt_i32_e32 vcc, s84, v80
	v_cmp_gt_i32_e64 s[6:7], s88, v80
	s_or_b64 vcc, vcc, s[6:7]
	v_subrev_u32_e32 v80, 53, v215
	v_cndmask_b32_e32 v89, v89, v203, vcc
	v_cmp_lt_i32_e32 vcc, s84, v80
	v_cmp_gt_i32_e64 s[6:7], s88, v80
	s_or_b64 vcc, vcc, s[6:7]
	v_add_u32_e32 v80, 0xffffffab, v215
	v_cndmask_b32_e32 v106, v106, v203, vcc
	v_cmp_lt_i32_e32 vcc, s84, v80
	v_cmp_gt_i32_e64 s[6:7], s88, v80
	s_or_b64 vcc, vcc, s[6:7]
	v_subrev_u32_e32 v80, 54, v215
	v_cndmask_b32_e32 v90, v90, v203, vcc
	v_cmp_lt_i32_e32 vcc, s84, v80
	v_cmp_gt_i32_e64 s[6:7], s88, v80
	s_or_b64 vcc, vcc, s[6:7]
	v_add_u32_e32 v80, 0xffffffaa, v215
	v_cndmask_b32_e32 v107, v107, v203, vcc
	v_cmp_lt_i32_e32 vcc, s84, v80
	v_cmp_gt_i32_e64 s[6:7], s88, v80
	s_or_b64 vcc, vcc, s[6:7]
	v_subrev_u32_e32 v80, 55, v215
	v_cndmask_b32_e32 v91, v91, v203, vcc
	v_cmp_lt_i32_e32 vcc, s84, v80
	v_cmp_gt_i32_e64 s[6:7], s88, v80
	s_or_b64 vcc, vcc, s[6:7]
	v_add_u32_e32 v80, 0xffffffa9, v215
	v_cndmask_b32_e32 v108, v108, v203, vcc
	v_cmp_lt_i32_e32 vcc, s84, v80
	v_cmp_gt_i32_e64 s[6:7], s88, v80
	s_or_b64 vcc, vcc, s[6:7]
	v_subrev_u32_e32 v80, 56, v215
	v_cndmask_b32_e32 v92, v92, v203, vcc
	v_cmp_lt_i32_e32 vcc, s84, v80
	v_cmp_gt_i32_e64 s[6:7], s88, v80
	s_or_b64 vcc, vcc, s[6:7]
	v_add_u32_e32 v80, 0xffffffa8, v215
	v_cndmask_b32_e32 v109, v109, v203, vcc
	v_cmp_lt_i32_e32 vcc, s84, v80
	v_cmp_gt_i32_e64 s[6:7], s88, v80
	s_or_b64 vcc, vcc, s[6:7]
	v_subrev_u32_e32 v80, 61, v215
	v_cndmask_b32_e32 v93, v93, v203, vcc
	v_cmp_lt_i32_e32 vcc, s84, v80
	v_cmp_gt_i32_e64 s[6:7], s88, v80
	s_or_b64 vcc, vcc, s[6:7]
	v_add_u32_e32 v80, 0xffffffa3, v215
	v_cndmask_b32_e32 v110, v110, v203, vcc
	v_cmp_lt_i32_e32 vcc, s84, v80
	v_cmp_gt_i32_e64 s[6:7], s88, v80
	s_or_b64 vcc, vcc, s[6:7]
	v_subrev_u32_e32 v80, 62, v215
	v_cndmask_b32_e32 v94, v94, v203, vcc
	v_cmp_lt_i32_e32 vcc, s84, v80
	v_cmp_gt_i32_e64 s[6:7], s88, v80
	s_or_b64 vcc, vcc, s[6:7]
	v_add_u32_e32 v80, 0xffffffa2, v215
	v_cndmask_b32_e32 v111, v111, v203, vcc
	v_cmp_lt_i32_e32 vcc, s84, v80
	v_cmp_gt_i32_e64 s[6:7], s88, v80
	s_or_b64 vcc, vcc, s[6:7]
	v_subrev_u32_e32 v80, 63, v215
	v_cndmask_b32_e32 v95, v95, v203, vcc
	v_cmp_lt_i32_e32 vcc, s84, v80
	v_cmp_gt_i32_e64 s[6:7], s88, v80
	s_or_b64 vcc, vcc, s[6:7]
	v_add_u32_e32 v80, 0xffffffa1, v215
	v_cndmask_b32_e32 v112, v112, v203, vcc
	v_cmp_lt_i32_e32 vcc, s84, v80
	v_cmp_gt_i32_e64 s[6:7], s88, v80
	s_or_b64 vcc, vcc, s[6:7]
	v_subrev_u32_e32 v80, 64, v215
	v_cndmask_b32_e32 v96, v96, v203, vcc
	v_cmp_lt_i32_e32 vcc, s84, v80
	v_cmp_gt_i32_e64 s[6:7], s88, v80
	s_or_b64 vcc, vcc, s[6:7]
	v_add_u32_e32 v80, 0xffffffa0, v215
	v_cndmask_b32_e32 v113, v113, v203, vcc
	v_cmp_lt_i32_e32 vcc, s84, v80
	v_cmp_gt_i32_e64 s[6:7], s88, v80
	s_or_b64 vcc, vcc, s[6:7]
	v_cndmask_b32_e32 v97, v97, v203, vcc
.LBB0_598:
	v_fmamk_f32 v67, v67, 0x3e0293ee, v227
	v_fmamk_f32 v69, v69, 0x3e0293ee, v227
	v_fmamk_f32 v71, v71, 0x3e0293ee, v227
	v_fmamk_f32 v73, v73, 0x3e0293ee, v227
	v_fmamk_f32 v75, v75, 0x3e0293ee, v227
	v_fmamk_f32 v77, v77, 0x3e0293ee, v227
	v_fmamk_f32 v79, v79, 0x3e0293ee, v227
	v_fmac_f32_e32 v227, 0x3e0293ee, v81
	v_exp_f32_e32 v245, v227
	v_add_f32_e32 v227, 0, v72
	v_add_f32_e32 v227, v217, v227
	v_add_f32_e32 v227, v218, v227
	v_add_f32_e32 v227, v221, v227
	v_add_f32_e32 v227, v222, v227
	v_add_f32_e32 v227, v224, v227
	v_add_f32_e32 v227, v225, v227
	v_add_f32_e32 v227, v226, v227
	v_add_f32_e32 v227, v66, v227
	v_add_f32_e32 v227, v68, v227
	v_add_f32_e32 v227, v70, v227
	v_add_f32_e32 v227, v74, v227
	v_exp_f32_e32 v80, v234
	v_add_f32_e32 v227, v216, v227
	v_exp_f32_e32 v67, v67
	v_add_f32_e32 v227, v219, v227
	v_exp_f32_e32 v81, v231
	v_add_f32_e32 v227, v220, v227
	v_exp_f32_e32 v69, v69
	v_add_f32_e32 v227, v223, v227
	v_exp_f32_e32 v234, v230
	v_add_f32_e32 v227, v80, v227
	v_exp_f32_e32 v71, v71
	v_add_f32_e32 v227, v67, v227
	v_exp_f32_e32 v242, v229
	v_add_f32_e32 v227, v81, v227
	v_exp_f32_e32 v73, v73
	v_add_f32_e32 v227, v69, v227
	v_exp_f32_e32 v243, v228
	v_add_f32_e32 v227, v234, v227
	v_exp_f32_e32 v75, v75
	v_add_f32_e32 v227, v71, v227
	v_exp_f32_e32 v244, v236
	v_add_f32_e32 v227, v242, v227
	v_exp_f32_e32 v77, v77
	v_add_f32_e32 v227, v73, v227
	v_exp_f32_e32 v78, v78
	v_add_f32_e32 v227, v243, v227
	v_exp_f32_e32 v79, v79
	v_add_f32_e32 v227, v75, v227
	v_exp_f32_e32 v76, v76
	v_add_f32_e32 v227, v244, v227
	v_add_f32_e32 v227, v77, v227
	v_add_f32_e32 v227, v78, v227
	v_add_f32_e32 v227, v79, v227
	v_add_f32_e32 v227, v76, v227
	v_add_f32_e32 v236, v245, v227
	v_mov_b32_e32 v237, v236
	v_cvt_pk_bf16_f32 v229, v218, v221
	v_cvt_pk_bf16_f32 v231, v225, v226
	v_cvt_pk_bf16_f32 v226, v216, v219
	v_cvt_pk_bf16_f32 v216, v80, v67
	v_cvt_pk_bf16_f32 v218, v234, v71
	v_permlane32_swap_b32_e32 v236, v237
	v_cvt_pk_bf16_f32 v228, v72, v217
	v_cvt_pk_bf16_f32 v230, v222, v224
	v_cvt_pk_bf16_f32 v224, v66, v68
	v_cvt_pk_bf16_f32 v225, v70, v74
	v_cvt_pk_bf16_f32 v227, v220, v223
	v_cvt_pk_bf16_f32 v217, v81, v69
	v_cvt_pk_bf16_f32 v219, v242, v73
	v_permlane32_swap_b32_e32 v216, v218
	v_cvt_pk_bf16_f32 v220, v243, v75
	v_cvt_pk_bf16_f32 v221, v244, v77
	v_cvt_pk_bf16_f32 v222, v78, v79
	v_cvt_pk_bf16_f32 v223, v76, v245
	v_permlane32_swap_b32_e32 v228, v230
	v_permlane32_swap_b32_e32 v229, v231
	v_permlane32_swap_b32_e32 v224, v226
	v_permlane32_swap_b32_e32 v225, v227
	v_permlane32_swap_b32_e32 v217, v219
	v_permlane32_swap_b32_e32 v220, v222
	v_permlane32_swap_b32_e32 v221, v223
	v_lshl_add_u64 v[66:67], v[148:149], 0, s[22:23]
	v_lshl_add_u64 v[70:71], v[150:151], 0, s[22:23]
	v_lshl_add_u64 v[74:75], v[152:153], 0, s[22:23]
	v_lshl_add_u64 v[78:79], v[154:155], 0, s[22:23]
	global_load_dwordx4 v[66:69], v[66:67], off
	s_nop 0
	global_load_dwordx4 v[70:73], v[70:71], off
	s_nop 0
	global_load_dwordx4 v[74:77], v[74:75], off
	s_nop 0
	global_load_dwordx4 v[78:81], v[78:79], off
	ds_read_b64_tr_b16 v[242:243], v214 offset:0
	ds_read_b64_tr_b16 v[244:245], v214 offset:2048
	ds_read_b64_tr_b16 v[246:247], v214 offset:4096
	ds_read_b64_tr_b16 v[248:249], v214 offset:6144
	ds_read_b64_tr_b16 v[196:197], v214 offset:8192
	ds_read_b64_tr_b16 v[198:199], v214 offset:10240
	s_waitcnt lgkmcnt(4)
	v_mfma_f32_32x32x16_bf16 v[50:65], v[228:231], v[242:245], v[50:65]
	ds_read_b64_tr_b16 v[238:239], v214 offset:12288
	ds_read_b64_tr_b16 v[240:241], v214 offset:14336
	s_waitcnt lgkmcnt(4)
	v_mfma_f32_32x32x16_bf16 v[50:65], v[224:227], v[246:249], v[50:65]
	ds_read_b64_tr_b16 v[242:243], v214 offset:512
	ds_read_b64_tr_b16 v[244:245], v214 offset:2560
	s_waitcnt lgkmcnt(4)
	v_mfma_f32_32x32x16_bf16 v[50:65], v[216:219], v[196:199], v[50:65]
	ds_read_b64_tr_b16 v[246:247], v214 offset:4608
	ds_read_b64_tr_b16 v[248:249], v214 offset:6656
	s_waitcnt lgkmcnt(4)
	v_mfma_f32_32x32x16_bf16 v[50:65], v[220:223], v[238:241], v[50:65]
	ds_read_b64_tr_b16 v[196:197], v214 offset:8704
	ds_read_b64_tr_b16 v[198:199], v214 offset:10752
	s_waitcnt lgkmcnt(4)
	v_mfma_f32_32x32x16_bf16 v[34:49], v[228:231], v[242:245], v[34:49]
	ds_read_b64_tr_b16 v[238:239], v214 offset:12800
	ds_read_b64_tr_b16 v[240:241], v214 offset:14848
	s_waitcnt lgkmcnt(4)
	v_mfma_f32_32x32x16_bf16 v[34:49], v[224:227], v[246:249], v[34:49]
	ds_read_b64_tr_b16 v[242:243], v214 offset:1024
	ds_read_b64_tr_b16 v[244:245], v214 offset:3072
	s_waitcnt lgkmcnt(4)
	v_mfma_f32_32x32x16_bf16 v[34:49], v[216:219], v[196:199], v[34:49]
	ds_read_b64_tr_b16 v[246:247], v214 offset:5120
	ds_read_b64_tr_b16 v[248:249], v214 offset:7168
	s_waitcnt lgkmcnt(4)
	v_mfma_f32_32x32x16_bf16 v[34:49], v[220:223], v[238:241], v[34:49]
	ds_read_b64_tr_b16 v[196:197], v214 offset:9216
	ds_read_b64_tr_b16 v[198:199], v214 offset:11264
	s_waitcnt lgkmcnt(4)
	v_mfma_f32_32x32x16_bf16 v[18:33], v[228:231], v[242:245], v[18:33]
	ds_read_b64_tr_b16 v[238:239], v214 offset:13312
	ds_read_b64_tr_b16 v[240:241], v214 offset:15360
	s_waitcnt lgkmcnt(4)
	v_mfma_f32_32x32x16_bf16 v[18:33], v[224:227], v[246:249], v[18:33]
	ds_read_b64_tr_b16 v[242:243], v214 offset:1536
	ds_read_b64_tr_b16 v[244:245], v214 offset:3584
	s_waitcnt lgkmcnt(4)
	v_mfma_f32_32x32x16_bf16 v[18:33], v[216:219], v[196:199], v[18:33]
	ds_read_b64_tr_b16 v[246:247], v214 offset:5632
	ds_read_b64_tr_b16 v[248:249], v214 offset:7680
	s_waitcnt lgkmcnt(4)
	v_mfma_f32_32x32x16_bf16 v[18:33], v[220:223], v[238:241], v[18:33]
	ds_read_b64_tr_b16 v[196:197], v214 offset:9728
	ds_read_b64_tr_b16 v[198:199], v214 offset:11776
	s_waitcnt lgkmcnt(4)
	v_mfma_f32_32x32x16_bf16 v[2:17], v[228:231], v[242:245], v[2:17]
	ds_read_b64_tr_b16 v[238:239], v214 offset:13824
	ds_read_b64_tr_b16 v[240:241], v214 offset:15872
	s_waitcnt lgkmcnt(4)
	v_mfma_f32_32x32x16_bf16 v[2:17], v[224:227], v[246:249], v[2:17]
	s_waitcnt lgkmcnt(2)
	v_mfma_f32_32x32x16_bf16 v[2:17], v[216:219], v[196:199], v[2:17]
	v_max_f32_e32 v216, v99, v99
	v_max_f32_e32 v217, v98, v98
	v_max_f32_e32 v216, v217, v216
	v_max3_f32 v216, v216, v100, v101
	v_max3_f32 v216, v216, v102, v103
	v_max3_f32 v216, v216, v104, v105
	v_max3_f32 v216, v216, v106, v107
	v_max3_f32 v216, v216, v108, v109
	v_max3_f32 v216, v216, v110, v111
	v_max3_f32 v216, v216, v112, v113
	v_max3_f32 v216, v216, v82, v83
	v_max3_f32 v216, v216, v84, v85
	v_max3_f32 v216, v216, v86, v87
	v_max3_f32 v216, v216, v88, v89
	v_max3_f32 v216, v216, v90, v91
	v_max3_f32 v216, v216, v92, v93
	v_max3_f32 v216, v216, v94, v95
	v_max3_f32 v216, v216, v96, v97
	v_mov_b32_e32 v217, v216
	s_nop 1
	v_permlane32_swap_b32_e32 v216, v217
	v_max_f32_e32 v217, v217, v217
	v_max_f32_e32 v216, v216, v216
	v_max_f32_e32 v216, v216, v217
	v_sub_f32_e32 v217, v216, v212
	v_cmp_ge_f32_e32 vcc, s40, v217
	v_max_f32_e32 v217, v212, v212
	v_max_f32_e32 v216, v217, v216
	s_waitcnt lgkmcnt(0)
	v_mfma_f32_32x32x16_bf16 v[2:17], v[220:223], v[238:241], v[2:17]
	v_sub_f32_e32 v217, v212, v216
	v_mul_f32_e32 v217, 0x3e0293ee, v217
	s_barrier
	s_waitcnt vmcnt(3)
	ds_write_b128 v208, v[66:69] offset:16384
	s_waitcnt vmcnt(2)
	ds_write_b128 v209, v[70:73] offset:16384
	s_waitcnt vmcnt(1)
	ds_write_b128 v210, v[74:77] offset:49152
	s_waitcnt vmcnt(0)
	ds_write_b128 v211, v[78:81] offset:49152
	v_exp_f32_e32 v66, v217
	s_cmp_eq_u64 vcc, exec
	s_cselect_b64 s[6:7], -1, 0
	v_cndmask_b32_e64 v234, v66, 1.0, s[6:7]
	v_cmp_gt_f32_e32 vcc, 1.0, v234
	s_cbranch_vccz .LBB0_602
	s_and_saveexec_b64 s[8:9], s[4:5]
	ds_write_b32 v183, v234 offset:128
	s_or_b64 exec, exec, s[8:9]
	s_waitcnt lgkmcnt(0)
	v_add_u32_e32 v78, v181, v146
	ds_read_b128 v[66:69], v78 offset:224
	ds_read_b128 v[70:73], v78 offset:192
	ds_read_b128 v[74:77], v78 offset:128
	ds_read_b128 v[78:81], v78 offset:160
	s_waitcnt lgkmcnt(3)
	v_pk_mul_f32 v[64:65], v[64:65], v[68:69]
	v_pk_mul_f32 v[62:63], v[62:63], v[66:67]
	s_waitcnt lgkmcnt(2)
	v_pk_mul_f32 v[60:61], v[60:61], v[72:73]
	v_pk_mul_f32 v[58:59], v[58:59], v[70:71]
	s_waitcnt lgkmcnt(0)
	v_pk_mul_f32 v[56:57], v[56:57], v[80:81]
	v_pk_mul_f32 v[54:55], v[54:55], v[78:79]
	v_pk_mul_f32 v[52:53], v[52:53], v[76:77]
	v_pk_mul_f32 v[50:51], v[50:51], v[74:75]
	v_pk_mul_f32 v[48:49], v[48:49], v[68:69]
	v_pk_mul_f32 v[46:47], v[46:47], v[66:67]
	v_pk_mul_f32 v[44:45], v[44:45], v[72:73]
	v_pk_mul_f32 v[42:43], v[42:43], v[70:71]
	v_pk_mul_f32 v[40:41], v[40:41], v[80:81]
	v_pk_mul_f32 v[38:39], v[38:39], v[78:79]
	v_pk_mul_f32 v[36:37], v[36:37], v[76:77]
	v_pk_mul_f32 v[34:35], v[34:35], v[74:75]
	v_pk_mul_f32 v[32:33], v[32:33], v[68:69]
	v_pk_mul_f32 v[30:31], v[30:31], v[66:67]
	v_pk_mul_f32 v[28:29], v[28:29], v[72:73]
	v_pk_mul_f32 v[26:27], v[26:27], v[70:71]
	v_pk_mul_f32 v[24:25], v[24:25], v[80:81]
	v_pk_mul_f32 v[22:23], v[22:23], v[78:79]
	v_pk_mul_f32 v[20:21], v[20:21], v[76:77]
	v_pk_mul_f32 v[18:19], v[18:19], v[74:75]
	v_pk_mul_f32 v[16:17], v[16:17], v[68:69]
	v_pk_mul_f32 v[14:15], v[14:15], v[66:67]
	v_pk_mul_f32 v[12:13], v[12:13], v[72:73]
	v_pk_mul_f32 v[10:11], v[10:11], v[70:71]
	v_pk_mul_f32 v[8:9], v[8:9], v[80:81]
	v_pk_mul_f32 v[6:7], v[6:7], v[78:79]
	v_pk_mul_f32 v[4:5], v[4:5], v[76:77]
	v_pk_mul_f32 v[2:3], v[2:3], v[74:75]

.LBB0_666:
	v_mov_b64_e32 v[168:169], 0x17f
	v_mov_b64_e32 v[170:171], 0x200
	v_mov_b64_e32 v[172:173], 0x1ff
	v_mov_b64_e32 v[174:175], 0x800
	v_mov_b32_e32 v196, 0xbab64f3b
	v_mbcnt_lo_u32_b32 v197, -1, 0
	v_mbcnt_hi_u32_b32 v197, -1, v197
	v_mov_b32_e32 v198, 0x42800000
	v_not_b32_e32 v199, 63
	v_mov_b32_e32 v238, 0
	v_mov_b32_e32 v239, 0
	v_mov_b32_e32 v240, 0
	v_mov_b32_e32 v241, 0
	s_mov_b64 s[6:7], s[0:1]
	s_mov_b32 s4, s2
	s_getreg_b32 s8, hwreg(HW_REG_XCC_ID, 0, 4)
	s_waitcnt vmcnt(0)
	s_barrier
	s_mov_b64 s[4:5], exec
	v_readlane_b32 s10, v254, 0
	v_readlane_b32 s11, v254, 1
	s_and_b64 s[10:11], s[4:5], s[10:11]
	v_readlane_b32 s29, v254, 3
	s_mov_b32 s49, 0x100000
	s_mov_b64 exec, s[10:11]
	s_cbranch_execz .LBB0_719
	v_readlane_b32 s9, v254, 4
	s_load_dwordx2 s[6:7], s[6:7], 0xb0
	s_waitcnt vmcnt(0) expcnt(0) lgkmcnt(0)
	v_mov_b32_e32 v1, s9
	ds_read_b32 v3, v1
	v_readlane_b32 s9, v254, 5
	s_and_b32 s26, s8, 15
	s_waitcnt lgkmcnt(0)
	v_cmp_ne_u32_e32 vcc, 0, v3
	v_mov_b32_e32 v1, s9
	ds_read_b32 v2, v1
	s_cbranch_vccnz .LBB0_683
	s_add_u32 s8, s6, 0x2c080200
	s_addc_u32 s9, s7, 0
	s_add_u32 s10, s6, 0x2c080400
	s_addc_u32 s11, s7, 0
	s_add_u32 s12, s6, 0x2c080500
	s_addc_u32 s13, s7, 0
	s_add_u32 s16, s6, 0x2c080600
	s_addc_u32 s17, s7, 0
	s_add_u32 s18, s6, 0x2c080700
	s_addc_u32 s19, s7, 0
	s_add_u32 s20, s6, 0x2c080800
	s_addc_u32 s21, s7, 0
	s_add_u32 s22, s6, 0x2c080900
	s_addc_u32 s23, s7, 0
	s_add_u32 s60, s6, 0x2c080a00
	s_addc_u32 s61, s7, 0
	s_add_u32 s66, s6, 0x2c080b00
	s_addc_u32 s67, s7, 0
	s_add_u32 s68, s6, 0x2c080c00
	s_addc_u32 s69, s7, 0
	s_add_u32 s70, s6, 0x2c080d00
	s_addc_u32 s71, s7, 0
	s_add_u32 s72, s6, 0x2c080e00
	s_addc_u32 s73, s7, 0
	s_add_u32 s74, s6, 0x2c080f00
	s_addc_u32 s75, s7, 0
	s_add_u32 s76, s6, 0x2c081000
	s_addc_u32 s77, s7, 0
	s_add_u32 s78, s6, 0x2c081100
	s_addc_u32 s79, s7, 0
	s_add_u32 s80, s6, 0x2c081200
	s_addc_u32 s81, s7, 0
	s_add_u32 s82, s6, 0x2c081300
	s_addc_u32 s83, s7, 0
	s_mov_b32 s29, 1
	s_branch .LBB0_671

.LBB0_1035:
	s_add_u32 s46, s64, 0xfff80080
	s_addc_u32 s47, s65, -1
	s_add_i32 s48, 0, 0x10000
	s_cmp_eq_u32 s84, 28
	s_cselect_b32 s67, s17, s47
	s_cselect_b32 s66, s80, s46
	v_add_u32_e32 v140, s48, v142
	s_cselect_b32 s61, s13, s83
	s_cselect_b32 s60, s81, s82
	s_add_i32 s49, 0, 0x14000
	ds_read_b128 v[146:149], v140
	ds_read_b128 v[150:153], v140 offset:1024
	ds_read_b128 v[154:157], v140 offset:2048
	ds_read_b128 v[158:161], v140 offset:3072
	v_add_u32_e32 v140, s49, v142
	ds_read_b128 v[162:165], v140
	ds_read_b128 v[178:181], v140 offset:1024
	ds_read_b128 v[182:185], v140 offset:2048
	ds_read_b128 v[186:189], v140 offset:3072
	s_add_i32 m0, s23, 0xc000
	ds_read_b128 v[206:209], v144
	ds_read_b128 v[210:213], v144 offset:1024
	ds_read_b128 v[214:217], v144 offset:2048
	ds_read_b128 v[218:221], v144 offset:3072
	ds_read_b128 v[222:225], v144 offset:4096
	ds_read_b128 v[226:229], v144 offset:5120
	ds_read_b128 v[230:233], v144 offset:6144
	ds_read_b128 v[234:237], v144 offset:7168
	global_load_lds_dwordx4 v136, s[64:65]
	s_add_i32 m0, s23, 0xe000
	s_nop 0
	global_load_lds_dwordx4 v138, s[64:65]
	s_waitcnt vmcnt(8)
	s_waitcnt lgkmcnt(0)
	s_barrier
	s_setprio 1
	s_waitcnt lgkmcnt(0)
	v_mfma_f32_16x16x32_bf16 v[126:129], v[146:149], v[206:209], v[126:129]
	v_mfma_f32_16x16x32_bf16 v[122:125], v[154:157], v[206:209], v[122:125]
	v_mfma_f32_16x16x32_bf16 v[110:113], v[146:149], v[214:217], v[110:113]
	v_mfma_f32_16x16x32_bf16 v[106:109], v[154:157], v[214:217], v[106:109]
	v_mfma_f32_16x16x32_bf16 v[94:97], v[146:149], v[222:225], v[94:97]
	v_mfma_f32_16x16x32_bf16 v[90:93], v[154:157], v[222:225], v[90:93]
	v_mfma_f32_16x16x32_bf16 v[78:81], v[146:149], v[230:233], v[78:81]
	v_mfma_f32_16x16x32_bf16 v[74:77], v[154:157], v[230:233], v[74:77]
	v_mfma_f32_16x16x32_bf16 v[126:129], v[150:153], v[210:213], v[126:129]
	v_mfma_f32_16x16x32_bf16 v[122:125], v[158:161], v[210:213], v[122:125]
	v_mfma_f32_16x16x32_bf16 v[110:113], v[150:153], v[218:221], v[110:113]
	v_mfma_f32_16x16x32_bf16 v[106:109], v[158:161], v[218:221], v[106:109]
	v_mfma_f32_16x16x32_bf16 v[94:97], v[150:153], v[226:229], v[94:97]
	v_mfma_f32_16x16x32_bf16 v[90:93], v[158:161], v[226:229], v[90:93]
	v_mfma_f32_16x16x32_bf16 v[78:81], v[150:153], v[234:237], v[78:81]
	v_mfma_f32_16x16x32_bf16 v[74:77], v[158:161], v[234:237], v[74:77]
	s_setprio 0
	s_setprio 1
	v_mfma_f32_16x16x32_bf16 v[118:121], v[162:165], v[206:209], v[118:121]
	v_mfma_f32_16x16x32_bf16 v[114:117], v[182:185], v[206:209], v[114:117]
	v_mfma_f32_16x16x32_bf16 v[102:105], v[162:165], v[214:217], v[102:105]
	v_mfma_f32_16x16x32_bf16 v[98:101], v[182:185], v[214:217], v[98:101]
	v_mfma_f32_16x16x32_bf16 v[86:89], v[162:165], v[222:225], v[86:89]
	v_mfma_f32_16x16x32_bf16 v[82:85], v[182:185], v[222:225], v[82:85]
	v_mfma_f32_16x16x32_bf16 v[70:73], v[162:165], v[230:233], v[70:73]
	v_mfma_f32_16x16x32_bf16 v[66:69], v[182:185], v[230:233], v[66:69]
	v_mfma_f32_16x16x32_bf16 v[118:121], v[178:181], v[210:213], v[118:121]
	v_mfma_f32_16x16x32_bf16 v[114:117], v[186:189], v[210:213], v[114:117]
	v_mfma_f32_16x16x32_bf16 v[102:105], v[178:181], v[218:221], v[102:105]
	v_mfma_f32_16x16x32_bf16 v[98:101], v[186:189], v[218:221], v[98:101]
	v_mfma_f32_16x16x32_bf16 v[86:89], v[178:181], v[226:229], v[86:89]
	v_mfma_f32_16x16x32_bf16 v[82:85], v[186:189], v[226:229], v[82:85]
	v_mfma_f32_16x16x32_bf16 v[70:73], v[178:181], v[234:237], v[70:73]
	v_mfma_f32_16x16x32_bf16 v[66:69], v[186:189], v[234:237], v[66:69]
	s_setprio 0
	s_barrier
	s_add_i32 s46, s48, s72
	s_mov_b32 m0, s46
	ds_read_b128 v[206:209], v144 offset:16384
	ds_read_b128 v[210:213], v144 offset:17408
	ds_read_b128 v[214:217], v144 offset:18432
	ds_read_b128 v[218:221], v144 offset:19456
	ds_read_b128 v[222:225], v144 offset:20480
	ds_read_b128 v[226:229], v144 offset:21504
	ds_read_b128 v[230:233], v144 offset:22528
	ds_read_b128 v[234:237], v144 offset:23552
	global_load_lds_dwordx4 v166, s[60:61]
	s_add_i32 m0, s46, 0x2000
	s_add_u32 s46, s60, 0x80000
	s_addc_u32 s47, s61, 0
	s_add_i32 s48, s49, s72
	global_load_lds_dwordx4 v134, s[60:61]
	s_mov_b32 m0, s48
	s_nop 0
	global_load_lds_dwordx4 v166, s[46:47]
	s_waitcnt vmcnt(5)
	s_waitcnt lgkmcnt(0)
	s_barrier
	s_setprio 1
	s_waitcnt lgkmcnt(0)
	v_mfma_f32_16x16x32_bf16 v[62:65], v[146:149], v[206:209], v[62:65]
	v_mfma_f32_16x16x32_bf16 v[58:61], v[154:157], v[206:209], v[58:61]
	v_mfma_f32_16x16x32_bf16 v[46:49], v[146:149], v[214:217], v[46:49]
	v_mfma_f32_16x16x32_bf16 v[42:45], v[154:157], v[214:217], v[42:45]
	v_mfma_f32_16x16x32_bf16 v[30:33], v[146:149], v[222:225], v[30:33]
	v_mfma_f32_16x16x32_bf16 v[26:29], v[154:157], v[222:225], v[26:29]
	s_add_i32 m0, s48, 0x2000
	s_nop 0
	global_load_lds_dwordx4 v134, s[46:47]
	v_mfma_f32_16x16x32_bf16 v[14:17], v[146:149], v[230:233], v[14:17]
	v_mfma_f32_16x16x32_bf16 v[10:13], v[154:157], v[230:233], v[10:13]
	v_mfma_f32_16x16x32_bf16 v[62:65], v[150:153], v[210:213], v[62:65]
	v_mfma_f32_16x16x32_bf16 v[58:61], v[158:161], v[210:213], v[58:61]
	v_mfma_f32_16x16x32_bf16 v[46:49], v[150:153], v[218:221], v[46:49]
	v_mfma_f32_16x16x32_bf16 v[42:45], v[158:161], v[218:221], v[42:45]
	v_mfma_f32_16x16x32_bf16 v[30:33], v[150:153], v[226:229], v[30:33]
	v_mfma_f32_16x16x32_bf16 v[26:29], v[158:161], v[226:229], v[26:29]
	v_mfma_f32_16x16x32_bf16 v[14:17], v[150:153], v[234:237], v[14:17]
	v_mfma_f32_16x16x32_bf16 v[10:13], v[158:161], v[234:237], v[10:13]
	s_mov_b32 m0, s23
	s_nop 0
	global_load_lds_dwordx4 v130, s[66:67]
	s_setprio 0
	s_setprio 1
	v_mfma_f32_16x16x32_bf16 v[54:57], v[162:165], v[206:209], v[54:57]
	v_mfma_f32_16x16x32_bf16 v[50:53], v[182:185], v[206:209], v[50:53]
	v_mfma_f32_16x16x32_bf16 v[38:41], v[162:165], v[214:217], v[38:41]
	v_mfma_f32_16x16x32_bf16 v[34:37], v[182:185], v[214:217], v[34:37]
	v_mfma_f32_16x16x32_bf16 v[22:25], v[162:165], v[222:225], v[22:25]
	v_mfma_f32_16x16x32_bf16 v[18:21], v[182:185], v[222:225], v[18:21]
	v_mfma_f32_16x16x32_bf16 v[6:9], v[162:165], v[230:233], v[6:9]
	v_mfma_f32_16x16x32_bf16 v[2:5], v[182:185], v[230:233], v[2:5]
	v_mfma_f32_16x16x32_bf16 v[54:57], v[178:181], v[210:213], v[54:57]
	v_mfma_f32_16x16x32_bf16 v[50:53], v[186:189], v[210:213], v[50:53]
	s_mov_b32 m0, s73
	s_nop 0
	global_load_lds_dwordx4 v132, s[66:67]
	v_mfma_f32_16x16x32_bf16 v[38:41], v[178:181], v[218:221], v[38:41]
	v_mfma_f32_16x16x32_bf16 v[34:37], v[186:189], v[218:221], v[34:37]
	v_mfma_f32_16x16x32_bf16 v[22:25], v[178:181], v[226:229], v[22:25]
	v_mfma_f32_16x16x32_bf16 v[18:21], v[186:189], v[226:229], v[18:21]
	v_mfma_f32_16x16x32_bf16 v[6:9], v[178:181], v[234:237], v[6:9]
	v_mfma_f32_16x16x32_bf16 v[2:5], v[186:189], v[234:237], v[2:5]
	s_setprio 0
	s_barrier
	s_add_i32 s48, 0, 0x18000
	v_add_u32_e32 v145, s48, v142
	s_add_i32 s49, 0, 0x1c000
	ds_read_b128 v[146:149], v145
	ds_read_b128 v[150:153], v145 offset:1024
	ds_read_b128 v[154:157], v145 offset:2048
	ds_read_b128 v[158:161], v145 offset:3072
	v_add_u32_e32 v145, s49, v142
	ds_read_b128 v[162:165], v145
	ds_read_b128 v[178:181], v145 offset:1024
	ds_read_b128 v[182:185], v145 offset:2048
	ds_read_b128 v[186:189], v145 offset:3072
	s_add_u32 s46, s66, 0x80000
	s_addc_u32 s47, s67, 0
	s_mov_b32 m0, s74
	ds_read_b128 v[206:209], v144 offset:32768
	ds_read_b128 v[210:213], v144 offset:33792
	ds_read_b128 v[214:217], v144 offset:34816
	ds_read_b128 v[218:221], v144 offset:35840
	ds_read_b128 v[222:225], v144 offset:36864
	ds_read_b128 v[226:229], v144 offset:37888
	ds_read_b128 v[230:233], v144 offset:38912
	ds_read_b128 v[234:237], v144 offset:39936
	global_load_lds_dwordx4 v130, s[46:47]
	s_mov_b32 m0, s75
	s_nop 0
	global_load_lds_dwordx4 v132, s[46:47]
	s_waitcnt vmcnt(8)
	s_waitcnt lgkmcnt(0)
	s_barrier
	s_setprio 1
	s_waitcnt lgkmcnt(0)
	v_mfma_f32_16x16x32_bf16 v[126:129], v[146:149], v[206:209], v[126:129]
	v_mfma_f32_16x16x32_bf16 v[122:125], v[154:157], v[206:209], v[122:125]
	v_mfma_f32_16x16x32_bf16 v[110:113], v[146:149], v[214:217], v[110:113]
	v_mfma_f32_16x16x32_bf16 v[106:109], v[154:157], v[214:217], v[106:109]
	v_mfma_f32_16x16x32_bf16 v[94:97], v[146:149], v[222:225], v[94:97]
	v_mfma_f32_16x16x32_bf16 v[90:93], v[154:157], v[222:225], v[90:93]
	v_mfma_f32_16x16x32_bf16 v[78:81], v[146:149], v[230:233], v[78:81]
	v_mfma_f32_16x16x32_bf16 v[74:77], v[154:157], v[230:233], v[74:77]
	v_mfma_f32_16x16x32_bf16 v[126:129], v[150:153], v[210:213], v[126:129]
	v_mfma_f32_16x16x32_bf16 v[122:125], v[158:161], v[210:213], v[122:125]
	v_mfma_f32_16x16x32_bf16 v[110:113], v[150:153], v[218:221], v[110:113]
	v_mfma_f32_16x16x32_bf16 v[106:109], v[158:161], v[218:221], v[106:109]
	v_mfma_f32_16x16x32_bf16 v[94:97], v[150:153], v[226:229], v[94:97]
	v_mfma_f32_16x16x32_bf16 v[90:93], v[158:161], v[226:229], v[90:93]
	v_mfma_f32_16x16x32_bf16 v[78:81], v[150:153], v[234:237], v[78:81]
	v_mfma_f32_16x16x32_bf16 v[74:77], v[158:161], v[234:237], v[74:77]
	s_setprio 0
	s_setprio 1
	v_mfma_f32_16x16x32_bf16 v[118:121], v[162:165], v[206:209], v[118:121]
	v_mfma_f32_16x16x32_bf16 v[114:117], v[182:185], v[206:209], v[114:117]
	v_mfma_f32_16x16x32_bf16 v[102:105], v[162:165], v[214:217], v[102:105]
	v_mfma_f32_16x16x32_bf16 v[98:101], v[182:185], v[214:217], v[98:101]
	v_mfma_f32_16x16x32_bf16 v[86:89], v[162:165], v[222:225], v[86:89]
	v_mfma_f32_16x16x32_bf16 v[82:85], v[182:185], v[222:225], v[82:85]
	v_mfma_f32_16x16x32_bf16 v[70:73], v[162:165], v[230:233], v[70:73]
	v_mfma_f32_16x16x32_bf16 v[66:69], v[182:185], v[230:233], v[66:69]
	v_mfma_f32_16x16x32_bf16 v[118:121], v[178:181], v[210:213], v[118:121]
	v_mfma_f32_16x16x32_bf16 v[114:117], v[186:189], v[210:213], v[114:117]
	v_mfma_f32_16x16x32_bf16 v[102:105], v[178:181], v[218:221], v[102:105]
	v_mfma_f32_16x16x32_bf16 v[98:101], v[186:189], v[218:221], v[98:101]
	v_mfma_f32_16x16x32_bf16 v[86:89], v[178:181], v[226:229], v[86:89]
	v_mfma_f32_16x16x32_bf16 v[82:85], v[186:189], v[226:229], v[82:85]
	v_mfma_f32_16x16x32_bf16 v[70:73], v[178:181], v[234:237], v[70:73]
	v_mfma_f32_16x16x32_bf16 v[66:69], v[186:189], v[234:237], v[66:69]
	s_setprio 0
	s_barrier
	s_add_i32 s46, s48, s72
	s_mov_b32 m0, s46
	ds_read_b128 v[206:209], v144 offset:49152
	ds_read_b128 v[210:213], v144 offset:50176
	ds_read_b128 v[214:217], v144 offset:51200
	ds_read_b128 v[218:221], v144 offset:52224
	ds_read_b128 v[222:225], v144 offset:53248
	ds_read_b128 v[226:229], v144 offset:54272
	ds_read_b128 v[230:233], v144 offset:55296
	ds_read_b128 v[234:237], v144 offset:56320
	s_add_u32 s100, s60, 128
	s_addc_u32 s101, s61, 0
	global_load_lds_dwordx4 v166, s[100:101]
	s_add_i32 m0, s46, 0x2000
	s_add_u32 s46, s60, 0x80080
	s_addc_u32 s47, s61, 0
	s_add_i32 s48, s49, s72
	s_add_u32 s100, s60, 128
	s_addc_u32 s101, s61, 0
	global_load_lds_dwordx4 v134, s[100:101]
	s_mov_b32 m0, s48
	s_nop 0
	global_load_lds_dwordx4 v166, s[46:47]
	s_waitcnt vmcnt(5)
	s_waitcnt lgkmcnt(0)
	s_barrier
	s_setprio 1
	s_waitcnt lgkmcnt(0)
	v_mfma_f32_16x16x32_bf16 v[62:65], v[146:149], v[206:209], v[62:65]
	v_mfma_f32_16x16x32_bf16 v[58:61], v[154:157], v[206:209], v[58:61]
	v_mfma_f32_16x16x32_bf16 v[46:49], v[146:149], v[214:217], v[46:49]
	v_mfma_f32_16x16x32_bf16 v[42:45], v[154:157], v[214:217], v[42:45]
	v_mfma_f32_16x16x32_bf16 v[30:33], v[146:149], v[222:225], v[30:33]
	v_mfma_f32_16x16x32_bf16 v[26:29], v[154:157], v[222:225], v[26:29]
	s_add_i32 m0, s48, 0x2000
	s_nop 0
	global_load_lds_dwordx4 v134, s[46:47]
	v_mfma_f32_16x16x32_bf16 v[14:17], v[146:149], v[230:233], v[14:17]
	v_mfma_f32_16x16x32_bf16 v[10:13], v[154:157], v[230:233], v[10:13]
	v_mfma_f32_16x16x32_bf16 v[62:65], v[150:153], v[210:213], v[62:65]
	v_mfma_f32_16x16x32_bf16 v[58:61], v[158:161], v[210:213], v[58:61]
	v_mfma_f32_16x16x32_bf16 v[46:49], v[150:153], v[218:221], v[46:49]
	v_mfma_f32_16x16x32_bf16 v[42:45], v[158:161], v[218:221], v[42:45]
	v_mfma_f32_16x16x32_bf16 v[30:33], v[150:153], v[226:229], v[30:33]
	v_mfma_f32_16x16x32_bf16 v[26:29], v[158:161], v[226:229], v[26:29]
	v_mfma_f32_16x16x32_bf16 v[14:17], v[150:153], v[234:237], v[14:17]
	v_mfma_f32_16x16x32_bf16 v[10:13], v[158:161], v[234:237], v[10:13]
	s_mov_b32 m0, s76
	s_nop 0
	s_add_u32 s100, s66, 128
	s_addc_u32 s101, s67, 0
	global_load_lds_dwordx4 v130, s[100:101]
	s_setprio 0
	s_setprio 1
	v_mfma_f32_16x16x32_bf16 v[54:57], v[162:165], v[206:209], v[54:57]
	v_mfma_f32_16x16x32_bf16 v[50:53], v[182:185], v[206:209], v[50:53]
	v_mfma_f32_16x16x32_bf16 v[38:41], v[162:165], v[214:217], v[38:41]
	v_mfma_f32_16x16x32_bf16 v[34:37], v[182:185], v[214:217], v[34:37]
	v_mfma_f32_16x16x32_bf16 v[22:25], v[162:165], v[222:225], v[22:25]
	v_mfma_f32_16x16x32_bf16 v[18:21], v[182:185], v[222:225], v[18:21]
	v_mfma_f32_16x16x32_bf16 v[6:9], v[162:165], v[230:233], v[6:9]
	v_mfma_f32_16x16x32_bf16 v[2:5], v[182:185], v[230:233], v[2:5]
	v_mfma_f32_16x16x32_bf16 v[54:57], v[178:181], v[210:213], v[54:57]
	v_mfma_f32_16x16x32_bf16 v[50:53], v[186:189], v[210:213], v[50:53]
	s_mov_b32 m0, s77
	s_nop 0
	s_add_u32 s100, s66, 128
	s_addc_u32 s101, s67, 0
	global_load_lds_dwordx4 v132, s[100:101]
	v_mfma_f32_16x16x32_bf16 v[38:41], v[178:181], v[218:221], v[38:41]
	v_mfma_f32_16x16x32_bf16 v[34:37], v[186:189], v[218:221], v[34:37]
	v_mfma_f32_16x16x32_bf16 v[22:25], v[178:181], v[226:229], v[22:25]
	v_mfma_f32_16x16x32_bf16 v[18:21], v[186:189], v[226:229], v[18:21]
	v_mfma_f32_16x16x32_bf16 v[6:9], v[178:181], v[234:237], v[6:9]
	v_mfma_f32_16x16x32_bf16 v[2:5], v[186:189], v[234:237], v[2:5]
	s_setprio 0
	s_barrier
	s_add_i32 s84, s84, 2
	s_add_u32 s64, s64, 0x100
	s_addc_u32 s65, s65, 0
	s_add_u32 s82, s82, 0x100
	s_addc_u32 s83, s83, 0
	s_cmp_gt_u32 s84, 29
	s_cbranch_scc0 .LBB0_1035
	s_and_b64 vcc, exec, s[10:11]
	s_cbranch_vccz .LBB0_1038
	s_barrier

	.amdhsa_kernel _Z10fwd_kernel4Args
		.amdhsa_group_segment_fixed_size 0
		.amdhsa_private_segment_fixed_size 0
		.amdhsa_kernarg_size 440
		.amdhsa_user_sgpr_count 2
		.amdhsa_user_sgpr_dispatch_ptr 0
		.amdhsa_user_sgpr_queue_ptr 0
		.amdhsa_user_sgpr_kernarg_segment_ptr 1
		.amdhsa_user_sgpr_dispatch_id 0
		.amdhsa_user_sgpr_kernarg_preload_length 0
		.amdhsa_user_sgpr_kernarg_preload_offset 0
		.amdhsa_user_sgpr_private_segment_size 0
		.amdhsa_uses_dynamic_stack 0
		.amdhsa_enable_private_segment 0
		.amdhsa_system_sgpr_workgroup_id_x 1
		.amdhsa_system_sgpr_workgroup_id_y 0
		.amdhsa_system_sgpr_workgroup_id_z 0
		.amdhsa_system_sgpr_workgroup_info 0
		.amdhsa_system_vgpr_workitem_id 0
		.amdhsa_next_free_vgpr 255
		.amdhsa_next_free_sgpr 102
		.amdhsa_accum_offset 256
		.amdhsa_reserve_vcc 1
		.amdhsa_float_round_mode_32 0
		.amdhsa_float_round_mode_16_64 0
		.amdhsa_float_denorm_mode_32 3
		.amdhsa_float_denorm_mode_16_64 3
		.amdhsa_dx10_clamp 1
		.amdhsa_ieee_mode 1
		.amdhsa_fp16_overflow 0
		.amdhsa_tg_split 0
		.amdhsa_exception_fp_ieee_invalid_op 0
		.amdhsa_exception_fp_denorm_src 0
		.amdhsa_exception_fp_ieee_div_zero 0
		.amdhsa_exception_fp_ieee_overflow 0
		.amdhsa_exception_fp_ieee_underflow 0
		.amdhsa_exception_fp_ieee_inexact 0
		.amdhsa_exception_int_div_zero 0
	.end_amdhsa_kernel

amdhsa.kernels:
  - .agpr_count:     0
    .args:
      - .offset:         0
        .size:           184
        .value_kind:     by_value
      - .offset:         184
        .size:           4
        .value_kind:     hidden_block_count_x
      - .offset:         188
        .size:           4
        .value_kind:     hidden_block_count_y
      - .offset:         192
        .size:           4
        .value_kind:     hidden_block_count_z
      - .offset:         196
        .size:           2
        .value_kind:     hidden_group_size_x
      - .offset:         198
        .size:           2
        .value_kind:     hidden_group_size_y
      - .offset:         200
        .size:           2
        .value_kind:     hidden_group_size_z
      - .offset:         202
        .size:           2
        .value_kind:     hidden_remainder_x
      - .offset:         204
        .size:           2
        .value_kind:     hidden_remainder_y
      - .offset:         206
        .size:           2
        .value_kind:     hidden_remainder_z
      - .offset:         224
        .size:           8
        .value_kind:     hidden_global_offset_x
      - .offset:         232
        .size:           8
        .value_kind:     hidden_global_offset_y
      - .offset:         240
        .size:           8
        .value_kind:     hidden_global_offset_z
      - .offset:         248
        .size:           2
        .value_kind:     hidden_grid_dims
      - .offset:         304
        .size:           4
        .value_kind:     hidden_dynamic_lds_size
    .group_segment_fixed_size: 0
    .kernarg_segment_align: 8
    .kernarg_segment_size: 440
    .language:       OpenCL C
    .language_version:
      - 2
      - 0
    .max_flat_workgroup_size: 512
    .name:           _Z10fwd_kernel4Args
    .private_segment_fixed_size: 0
    .sgpr_count:     108
    .sgpr_spill_count: 24
    .symbol:         _Z10fwd_kernel4Args.kd
    .uniform_work_group_size: 1
    .uses_dynamic_stack: false
    .vgpr_count:     255
    .vgpr_spill_count: 0
    .wavefront_size: 64
